# stack2 + x_prompt rows of each prompt-norm wave touched (L2/MALL prefetch) by waves 1-7 inside grid barrier 3
# baseline (speedup 1.0000x reference)
.LBB0_657:
	s_cbranch_execz .LBB0_628
	s_waitcnt vmcnt(0)
	s_and_b64 vcc, exec, s[72:73]
	s_waitcnt vmcnt(0)
	s_barrier
	s_cmp_lt_u32 s94, 64
	s_cbranch_scc1 .Lxpf_done
	v_readlane_b32 s98, v247, 11
	s_nop 3
	s_cmp_lt_u32 s98, 64
	s_cbranch_scc1 .Lxpf_done
	s_add_i32 s98, s98, -64
	s_lshl_b32 s98, s98, 3
	s_lshr_b32 s99, s94, 6
	s_add_i32 s98, s98, s99
	s_mov_b32 s101, 0
	v_mbcnt_lo_u32_b32 v248, -1, 0
	v_mbcnt_hi_u32_b32 v248, -1, v248
	v_lshlrev_b32_e32 v248, 7, v248
	v_mov_b32_e32 v249, 0
	v_lshl_add_u64 v[250:251], s[36:37], 0, v[248:249]
.Lxpf_loop:
	s_lshl_b32 s100, s98, 14
	v_lshl_add_u64 v[252:253], v[250:251], 0, s[100:101]
	global_load_dword v254, v[252:253], off
	s_add_i32 s100, s100, 0x2000
	v_lshl_add_u64 v[252:253], v[250:251], 0, s[100:101]
	global_load_dword v255, v[252:253], off
	s_addk_i32 s98, 0x600
	s_cmp_lt_u32 s98, 4096
	s_cbranch_scc1 .Lxpf_loop
.Lxpf_done:
	s_cbranch_vccnz .LBB0_712
	v_mbcnt_lo_u32_b32 v0, -1, 0
	v_mbcnt_hi_u32_b32 v0, -1, v0
	s_nop 0
	v_cmp_eq_u32_e32 vcc, 0, v0
	s_and_saveexec_b64 s[4:5], vcc
	s_cbranch_execz .LBB0_711
	s_add_i32 s0, 0, 0x20160
	v_mov_b32_e32 v0, s0
	s_waitcnt vmcnt(0) expcnt(0) lgkmcnt(0)
	ds_read_b32 v2, v0
	s_add_i32 s0, 0, 0x20164
	v_mov_b32_e32 v0, s0
	ds_read_b32 v0, v0
	s_waitcnt lgkmcnt(1)
	v_cmp_ne_u32_e32 vcc, 0, v2
	s_cbranch_vccnz .LBB0_675
	v_readlane_b32 s6, v247, 8
	v_readlane_b32 s7, v247, 9
	s_load_dwordx2 s[0:1], s[6:7], 0x4
	s_add_u32 s6, s66, 0x1400
	s_addc_u32 s7, s67, 0
	s_add_u32 s8, s66, 0x1500
	s_addc_u32 s9, s67, 0
	v_readlane_b32 s10, v247, 10
	s_waitcnt lgkmcnt(0)
	s_mul_i32 s0, s0, s10
	s_add_u32 s10, s66, 0x1600
	s_addc_u32 s11, s67, 0
	s_add_u32 s12, s66, 0x1700
	s_addc_u32 s13, s67, 0
	s_add_u32 s14, s66, 0x1800
	s_addc_u32 s15, s67, 0
	s_add_u32 s16, s66, 0x1900
	s_addc_u32 s17, s67, 0
	s_add_u32 s18, s66, 0x1a00
	s_addc_u32 s19, s67, 0
	s_add_u32 s22, s66, 0x1b00
	s_addc_u32 s23, s67, 0
	s_add_u32 s34, s66, 0x1c00
	s_addc_u32 s35, s67, 0
	s_add_u32 s40, s66, 0x1d00
	s_addc_u32 s41, s67, 0
	s_add_u32 s42, s66, 0x1e00
	s_addc_u32 s43, s67, 0
	s_add_u32 s44, s66, 0x1f00
	s_addc_u32 s45, s67, 0
	s_add_u32 s46, s66, 0x2000
	s_addc_u32 s47, s67, 0
	s_add_u32 s48, s66, 0x2100
	s_addc_u32 s49, s67, 0
	s_add_u32 s50, s66, 0x2200
	s_addc_u32 s51, s67, 0
	s_add_u32 s52, s66, 0x2300
	s_mul_i32 s0, s0, s1
	s_addc_u32 s53, s67, 0
	s_mov_b32 s1, 1
	v_mov_b32_e32 v16, 0
	s_branch .LBB0_663
